# scan loop: drop false-dependency vmcnt waits; attention final-pass epilogue: all loads issued up front with counted waits
# speedup vs baseline: 1.0018x; 1.0018x over previous
; __device__ __forceinline__ unsigned cvt_pk_bf16(float lo, float hi) { unsigned r; asm volatile("v_cvt_pk_bf16_f32 %0, %1, %2" : "=v"(r) : "v"(lo), "v"(hi)); return r; }
; __device__ __forceinline__ void ssm_scan(const Args& a, int sc, int lane) {
;     ...
;     for (int cb = 0; cb < nC; cb += 16) {
;         const int cn = cb + 16 < nC ? cb + 16 : cb;
; #pragma unroll
;         for (int q = 0; q < 16; ++q) { const int c = d == 0 ? cn + q : nC - 1 - (cn + q); nr_[q] = __uint_as_float((unsigned)E[(size_t)c * 256 + nb] << 16); ni_[q] = __uint_as_float((unsigned)E[(size_t)c * 256 + nb + 64] << 16); }
; #pragma unroll
;         for (int q = 0; q < 16; ++q) { const int c = d == 0 ? cb + q : nC - 1 - (cb + q);
;             H[(size_t)c * 256 + nb] = (bf16_t)(cvt_pk_bf16(hr, 0.f) & 0xffffu); H[(size_t)c * 256 + nb + 64] = (bf16_t)(cvt_pk_bf16(hi, 0.f) & 0xffffu);
;             const float nr = ar * hr - ai * hi + er[q], ni = ar * hi + ai * hr + ei[q]; hr = nr; hi = ni; }
; #pragma unroll
;         for (int q = 0; q < 16; ++q) { er[q] = nr_[q]; ei[q] = ni_[q]; }
;     }
.LBB0_588:
	s_add_i32 s24, s4, 16
	v_pk_mul_f32 v[50:51], v[4:5], v[12:13]
	v_pk_mul_f32 v[52:53], v[8:9], v[12:13]
	s_cmp_lt_u32 s24, s22
	v_sub_f32_e32 v32, v50, v51
	v_add_f32_e32 v50, v52, v53
	s_cselect_b64 s[12:13], -1, 0
	v_add_f32_e32 v32, v32, v30
	v_add_f32_e32 v30, v50, v36
	s_and_b64 s[26:27], s[12:13], exec
	v_pk_mul_f32 v[50:51], v[8:9], v[30:31] op_sel_hi:[1,0]
	s_cselect_b32 s25, s24, s4
	v_pk_fma_f32 v[52:53], v[4:5], v[32:33], v[50:51] neg_lo:[0,0,1] neg_hi:[0,0,1]
	v_pk_fma_f32 v[50:51], v[4:5], v[32:33], v[50:51] op_sel_hi:[1,0,1]
	s_not_b32 s26, s25
	v_mov_b32_e32 v53, v51
	s_add_i32 s28, s22, s26
	v_pk_add_f32 v[28:29], v[28:29], v[52:53]
	s_and_b64 s[26:27], s[6:7], exec
	v_pk_mul_f32 v[50:51], v[4:5], v[28:29]
	v_pk_mul_f32 v[52:53], v[4:5], v[28:29] op_sel:[0,1] op_sel_hi:[1,0]
	s_cselect_b32 s26, s25, s28
	s_xor_b32 s29, s25, -2
	v_sub_f32_e32 v36, v50, v51
	v_add_f32_e32 v50, v52, v53
	s_ashr_i32 s27, s26, 31
	s_or_b32 s28, s25, 1
	s_add_i32 s29, s29, s22
	v_add_f32_e32 v36, v34, v36
	v_add_f32_e32 v34, v40, v50
	s_lshl_b64 s[26:27], s[26:27], 9
	v_pk_mul_f32 v[50:51], v[8:9], v[34:35] op_sel_hi:[1,0]
	v_lshl_add_u64 v[52:53], v[6:7], 0, s[26:27]
	s_and_b64 s[26:27], s[6:7], exec
	v_pk_fma_f32 v[54:55], v[4:5], v[36:37], v[50:51] neg_lo:[0,0,1] neg_hi:[0,0,1]
	v_pk_fma_f32 v[50:51], v[4:5], v[36:37], v[50:51] op_sel_hi:[1,0,1]
	s_cselect_b32 s26, s28, s29
	s_xor_b32 s29, s25, -3
	v_mov_b32_e32 v55, v51
	s_ashr_i32 s27, s26, 31
	s_or_b32 s28, s25, 2
	s_add_i32 s29, s29, s22
	v_pk_add_f32 v[26:27], v[26:27], v[54:55]
	s_lshl_b64 s[26:27], s[26:27], 9
	v_pk_mul_f32 v[50:51], v[4:5], v[26:27]
	v_pk_mul_f32 v[54:55], v[4:5], v[26:27] op_sel:[0,1] op_sel_hi:[1,0]
	v_lshl_add_u64 v[56:57], v[6:7], 0, s[26:27]
	s_and_b64 s[26:27], s[6:7], exec
	v_sub_f32_e32 v40, v50, v51
	v_add_f32_e32 v50, v54, v55
	s_cselect_b32 s26, s28, s29
	s_xor_b32 s29, s25, -4
	v_add_f32_e32 v40, v38, v40
	v_add_f32_e32 v38, v44, v50
	s_ashr_i32 s27, s26, 31
	s_or_b32 s28, s25, 3
	s_add_i32 s29, s29, s22
	v_pk_mul_f32 v[50:51], v[8:9], v[38:39] op_sel_hi:[1,0]
	s_lshl_b64 s[26:27], s[26:27], 9
	global_load_ushort v70, v[52:53], off
	global_load_ushort v71, v[56:57], off
	global_load_ushort v72, v[56:57], off offset:128
	v_pk_fma_f32 v[54:55], v[4:5], v[40:41], v[50:51] neg_lo:[0,0,1] neg_hi:[0,0,1]
	v_pk_fma_f32 v[50:51], v[4:5], v[40:41], v[50:51] op_sel_hi:[1,0,1]
	v_lshl_add_u64 v[56:57], v[6:7], 0, s[26:27]
	s_and_b64 s[26:27], s[6:7], exec
	v_mov_b32_e32 v55, v51
	s_cselect_b32 s26, s28, s29
	s_xor_b32 s29, s25, -5
	v_pk_add_f32 v[24:25], v[24:25], v[54:55]
	s_ashr_i32 s27, s26, 31
	s_or_b32 s28, s25, 4
	s_add_i32 s29, s29, s22
	v_pk_mul_f32 v[50:51], v[4:5], v[24:25]
	v_pk_mul_f32 v[54:55], v[4:5], v[24:25] op_sel:[0,1] op_sel_hi:[1,0]
	s_lshl_b64 s[26:27], s[26:27], 9
	v_sub_f32_e32 v44, v50, v51
	v_add_f32_e32 v54, v54, v55
	v_lshl_add_u64 v[50:51], v[6:7], 0, s[26:27]
	s_and_b64 s[26:27], s[6:7], exec
	v_add_f32_e32 v44, v42, v44
	v_add_f32_e32 v42, v48, v54
	s_cselect_b32 s26, s28, s29
	global_load_ushort v73, v[56:57], off
	global_load_ushort v74, v[50:51], off
	global_load_ushort v75, v[50:51], off offset:128
	global_load_ushort v76, v[56:57], off offset:128
	global_load_ushort v77, v[52:53], off offset:128
	s_xor_b32 s29, s25, -6
	v_pk_mul_f32 v[50:51], v[8:9], v[42:43] op_sel_hi:[1,0]
	s_ashr_i32 s27, s26, 31
	s_or_b32 s28, s25, 5
	s_add_i32 s29, s29, s22
	v_pk_fma_f32 v[52:53], v[4:5], v[44:45], v[50:51] neg_lo:[0,0,1] neg_hi:[0,0,1]
	v_pk_fma_f32 v[50:51], v[4:5], v[44:45], v[50:51] op_sel_hi:[1,0,1]
	s_lshl_b64 s[26:27], s[26:27], 9
	v_mov_b32_e32 v53, v51
	v_lshl_add_u64 v[54:55], v[6:7], 0, s[26:27]
	s_and_b64 s[26:27], s[6:7], exec
	v_pk_add_f32 v[22:23], v[22:23], v[52:53]
	s_cselect_b32 s26, s28, s29
	v_pk_mul_f32 v[50:51], v[4:5], v[22:23]
	v_pk_mul_f32 v[52:53], v[4:5], v[22:23] op_sel:[0,1] op_sel_hi:[1,0]
	s_ashr_i32 s27, s26, 31
	v_sub_f32_e32 v48, v50, v51
	v_add_f32_e32 v50, v52, v53
	s_lshl_b64 s[26:27], s[26:27], 9
	v_add_f32_e32 v48, v46, v48
	v_add_f32_e32 v46, v49, v50
	v_lshl_add_u64 v[50:51], v[6:7], 0, s[26:27]
	global_load_ushort v78, v[54:55], off
	global_load_ushort v49, v[50:51], off
	global_load_ushort v79, v[50:51], off offset:128
	s_xor_b32 s29, s25, -7
	s_or_b32 s28, s25, 6
	s_add_i32 s29, s29, s22
	s_and_b64 s[26:27], s[6:7], exec
	v_pk_mul_f32 v[52:53], v[8:9], v[46:47] op_sel_hi:[1,0]
	s_cselect_b32 s26, s28, s29
	s_xor_b32 s29, s25, -8
	s_ashr_i32 s27, s26, 31
	s_or_b32 s28, s25, 7
	s_add_i32 s29, s29, s22
	s_lshl_b64 s[26:27], s[26:27], 9
	v_lshl_add_u64 v[56:57], v[6:7], 0, s[26:27]
	s_and_b64 s[26:27], s[6:7], exec
	s_cselect_b32 s26, s28, s29
	s_xor_b32 s29, s25, -9
	s_ashr_i32 s27, s26, 31
	s_or_b32 s28, s25, 8
	s_add_i32 s29, s29, s22
	s_lshl_b64 s[26:27], s[26:27], 9
	v_lshl_add_u64 v[60:61], v[6:7], 0, s[26:27]
	s_and_b64 s[26:27], s[6:7], exec
	s_cselect_b32 s26, s28, s29
	s_ashr_i32 s27, s26, 31
	s_lshl_b64 s[26:27], s[26:27], 9
	global_load_ushort v80, v[56:57], off
	s_xor_b32 s29, s25, -10
	s_or_b32 s28, s25, 9
	s_add_i32 s29, s29, s22
	v_pk_fma_f32 v[50:51], v[4:5], v[48:49], v[52:53] neg_lo:[0,0,1] neg_hi:[0,0,1]
	v_pk_fma_f32 v[52:53], v[4:5], v[48:49], v[52:53] op_sel_hi:[1,0,1]
	s_nop 0
	v_mov_b32_e32 v51, v53
	v_pk_add_f32 v[20:21], v[20:21], v[50:51]
	s_nop 0
	v_pk_mul_f32 v[50:51], v[4:5], v[20:21]
	v_pk_mul_f32 v[52:53], v[4:5], v[20:21] op_sel:[0,1] op_sel_hi:[1,0]
	v_sub_f32_e32 v50, v50, v51
	v_add_f32_e32 v51, v52, v53
	v_add_f32_e32 v52, v45, v50
	v_add_f32_e32 v50, v47, v51
	v_pk_mul_f32 v[58:59], v[4:5], v[50:51] op_sel_hi:[1,0]
	s_nop 0
	v_pk_fma_f32 v[62:63], v[8:9], v[52:53], v[58:59]
; __device__ __forceinline__ unsigned cvt_pk_bf16(float lo, float hi) { unsigned r; asm volatile("v_cvt_pk_bf16_f32 %0, %1, %2" : "=v"(r) : "v"(lo), "v"(hi)); return r; }
; __device__ __forceinline__ void ssm_scan(const Args& a, int sc, int lane) {
;     ...
;         for (int q = 0; q < 16; ++q) { const int c = d == 0 ? cn + q : nC - 1 - (cn + q); nr_[q] = __uint_as_float((unsigned)E[(size_t)c * 256 + nb] << 16); ni_[q] = __uint_as_float((unsigned)E[(size_t)c * 256 + nb + 64] << 16); }
; #pragma unroll
;         for (int q = 0; q < 16; ++q) { const int c = d == 0 ? cb + q : nC - 1 - (cb + q);
;             H[(size_t)c * 256 + nb] = (bf16_t)(cvt_pk_bf16(hr, 0.f) & 0xffffu); H[(size_t)c * 256 + nb + 64] = (bf16_t)(cvt_pk_bf16(hi, 0.f) & 0xffffu);
;             const float nr = ar * hr - ai * hi + er[q], ni = ar * hi + ai * hr + ei[q]; hr = nr; hi = ni; }
	v_pk_fma_f32 v[58:59], v[8:9], v[52:53], v[58:59] op_sel_hi:[1,0,1] neg_lo:[0,0,1] neg_hi:[0,0,1]
	global_load_ushort v45, v[60:61], off
	global_load_ushort v47, v[60:61], off offset:128
	global_load_ushort v51, v[56:57], off offset:128
	global_load_ushort v53, v[54:55], off offset:128
	v_mov_b32_e32 v63, v59
	v_pk_add_f32 v[18:19], v[18:19], v[62:63]
	v_lshl_add_u64 v[62:63], v[6:7], 0, s[26:27]
	v_pk_mul_f32 v[54:55], v[4:5], v[18:19] op_sel:[0,1] op_sel_hi:[1,0]
	v_pk_mul_f32 v[56:57], v[4:5], v[18:19]
	v_sub_f32_e32 v54, v54, v55
	v_add_f32_e32 v55, v56, v57
	global_load_ushort v57, v[62:63], off
	s_and_b64 s[26:27], s[6:7], exec
	s_cselect_b32 s26, s28, s29
	s_xor_b32 s29, s25, -11
	v_add_f32_e32 v56, v41, v54
	v_add_f32_e32 v54, v43, v55
	s_ashr_i32 s27, s26, 31
	s_or_b32 s28, s25, 10
	s_add_i32 s29, s29, s22
	v_pk_mul_f32 v[58:59], v[4:5], v[54:55] op_sel_hi:[1,0]
	s_lshl_b64 s[26:27], s[26:27], 9
	v_lshl_add_u64 v[64:65], v[6:7], 0, s[26:27]
	s_and_b64 s[26:27], s[6:7], exec
	s_cselect_b32 s26, s28, s29
	s_xor_b32 s29, s25, -12
	s_ashr_i32 s27, s26, 31
	s_or_b32 s28, s25, 11
	s_add_i32 s29, s29, s22
	s_lshl_b64 s[26:27], s[26:27], 9
	global_load_ushort v41, v[64:65], off
	global_load_ushort v43, v[64:65], off offset:128
	v_lshl_add_u64 v[64:65], v[6:7], 0, s[26:27]
	s_and_b64 s[26:27], s[6:7], exec
	s_cselect_b32 s26, s28, s29
	s_xor_b32 s29, s25, -13
	s_ashr_i32 s27, s26, 31
	s_or_b32 s28, s25, 12
	s_add_i32 s29, s29, s22
	s_lshl_b64 s[26:27], s[26:27], 9
	v_pk_fma_f32 v[60:61], v[8:9], v[56:57], v[58:59]
	v_pk_fma_f32 v[58:59], v[8:9], v[56:57], v[58:59] op_sel_hi:[1,0,1] neg_lo:[0,0,1] neg_hi:[0,0,1]
	s_nop 0
	v_mov_b32_e32 v61, v59
	v_pk_add_f32 v[16:17], v[16:17], v[60:61]
	s_nop 0
	v_pk_mul_f32 v[58:59], v[4:5], v[16:17] op_sel:[0,1] op_sel_hi:[1,0]
	v_pk_mul_f32 v[60:61], v[4:5], v[16:17]
	v_sub_f32_e32 v55, v58, v59
	v_add_f32_e32 v58, v60, v61
	v_add_f32_e32 v58, v39, v58
	v_add_f32_e32 v60, v37, v55
	v_pk_mul_f32 v[66:67], v[8:9], v[58:59] op_sel_hi:[1,0]
	global_load_ushort v37, v[64:65], off
	v_pk_fma_f32 v[68:69], v[4:5], v[60:61], v[66:67] neg_lo:[0,0,1] neg_hi:[0,0,1]
	v_pk_fma_f32 v[66:67], v[4:5], v[60:61], v[66:67] op_sel_hi:[1,0,1]
	s_nop 0
	v_mov_b32_e32 v69, v67
	v_lshl_add_u64 v[66:67], v[6:7], 0, s[26:27]
	s_and_b64 s[26:27], s[6:7], exec
	s_cselect_b32 s26, s28, s29
	s_xor_b32 s29, s25, -14
	s_ashr_i32 s27, s26, 31
	s_or_b32 s28, s25, 13
	s_add_i32 s29, s29, s22
	s_lshl_b64 s[26:27], s[26:27], 9
	global_load_ushort v39, v[66:67], off
	global_load_ushort v55, v[66:67], off offset:128
	global_load_ushort v59, v[64:65], off offset:128
	global_load_ushort v61, v[62:63], off offset:128
	v_lshl_add_u64 v[62:63], v[6:7], 0, s[26:27]
	s_and_b64 s[26:27], s[6:7], exec
	s_cselect_b32 s26, s28, s29
	s_xor_b32 s29, s25, -15
	s_ashr_i32 s27, s26, 31
	s_or_b32 s28, s25, 14
	s_add_i32 s29, s29, s22
	s_lshl_b64 s[26:27], s[26:27], 9
	v_lshl_add_u64 v[64:65], v[6:7], 0, s[26:27]
	s_and_b64 s[26:27], s[6:7], exec
	s_cselect_b32 s26, s28, s29
	s_or_b32 s28, s25, 15
	s_xor_b32 s25, s25, -16
	s_ashr_i32 s27, s26, 31
	s_add_i32 s25, s25, s22
	s_lshl_b64 s[26:27], s[26:27], 9
	global_load_ushort v81, v[62:63], off
	global_load_ushort v82, v[64:65], off
	global_load_ushort v83, v[64:65], off offset:128
	v_lshl_add_u64 v[64:65], v[6:7], 0, s[26:27]
	s_and_b64 s[26:27], s[6:7], exec
	s_cselect_b32 s26, s28, s25
	s_ashr_i32 s27, s26, 31
	s_lshl_b64 s[26:27], s[26:27], 9
	v_lshl_add_u64 v[66:67], v[6:7], 0, s[26:27]
	global_load_ushort v84, v[64:65], off
	global_load_ushort v85, v[66:67], off
	global_load_ushort v86, v[66:67], off offset:128
	global_load_ushort v87, v[64:65], off offset:128
	global_load_ushort v88, v[62:63], off offset:128
	s_and_b64 s[26:27], s[6:7], exec
	s_cselect_b32 s26, s4, s23
	s_xor_b32 s28, s4, -2
	s_ashr_i32 s27, s26, 31
	s_add_i32 s25, s4, 1
	s_add_i32 s28, s28, s22
	s_lshl_b64 s[26:27], s[26:27], 9
	v_lshl_add_u64 v[62:63], v[10:11], 0, s[26:27]
	s_and_b64 s[26:27], s[6:7], exec
	s_cselect_b32 s26, s25, s28
	s_xor_b32 s28, s4, -3
	s_ashr_i32 s27, s26, 31
	v_cvt_pk_bf16_f32 v12, v12, v35
	s_add_i32 s25, s4, 2
	s_add_i32 s28, s28, s22
	s_lshl_b64 s[26:27], s[26:27], 9
	global_store_short v[62:63], v12, off
	v_cvt_pk_bf16_f32 v64, v13, v35
	v_pk_add_f32 v[12:13], v[14:15], v[68:69]
	v_lshl_add_u64 v[14:15], v[10:11], 0, s[26:27]
	s_and_b64 s[26:27], s[6:7], exec
	s_cselect_b32 s26, s25, s28
	s_xor_b32 s28, s4, -4
	s_ashr_i32 s27, s26, 31
	s_add_i32 s25, s4, 3
	s_add_i32 s28, s28, s22
	s_lshl_b64 s[26:27], s[26:27], 9
	global_store_short v[62:63], v64, off offset:128
	v_cvt_pk_bf16_f32 v32, v32, v35
	global_store_short v[14:15], v32, off
	v_cvt_pk_bf16_f32 v30, v30, v35
	global_store_short v[14:15], v30, off offset:128
	v_lshl_add_u64 v[14:15], v[10:11], 0, s[26:27]
	s_and_b64 s[26:27], s[6:7], exec
	s_cselect_b32 s26, s25, s28
	s_xor_b32 s28, s4, -5
	s_ashr_i32 s27, s26, 31
	v_cvt_pk_bf16_f32 v28, v28, v35
	s_add_i32 s25, s4, 4
	s_add_i32 s28, s28, s22
	s_lshl_b64 s[26:27], s[26:27], 9
	global_store_short v[14:15], v28, off
	v_cvt_pk_bf16_f32 v28, v29, v35
	global_store_short v[14:15], v28, off offset:128
	v_lshl_add_u64 v[14:15], v[10:11], 0, s[26:27]
	s_and_b64 s[26:27], s[6:7], exec
	s_cselect_b32 s26, s25, s28
	s_xor_b32 s28, s4, -6
	s_ashr_i32 s27, s26, 31
	v_cvt_pk_bf16_f32 v28, v36, v35
	s_add_i32 s25, s4, 5
	s_add_i32 s28, s28, s22
	s_lshl_b64 s[26:27], s[26:27], 9
	global_store_short v[14:15], v28, off
	v_cvt_pk_bf16_f32 v28, v34, v35
	global_store_short v[14:15], v28, off offset:128
	v_lshl_add_u64 v[14:15], v[10:11], 0, s[26:27]
	s_and_b64 s[26:27], s[6:7], exec
	s_cselect_b32 s26, s25, s28
; __device__ __forceinline__ unsigned cvt_pk_bf16(float lo, float hi) { unsigned r; asm volatile("v_cvt_pk_bf16_f32 %0, %1, %2" : "=v"(r) : "v"(lo), "v"(hi)); return r; }
; __device__ __forceinline__ void ssm_scan(const Args& a, int sc, int lane) {
;     ...
;         for (int q = 0; q < 16; ++q) { const int c = d == 0 ? cb + q : nC - 1 - (cb + q);
;             H[(size_t)c * 256 + nb] = (bf16_t)(cvt_pk_bf16(hr, 0.f) & 0xffffu); H[(size_t)c * 256 + nb + 64] = (bf16_t)(cvt_pk_bf16(hi, 0.f) & 0xffffu);
;             const float nr = ar * hr - ai * hi + er[q], ni = ar * hi + ai * hr + ei[q]; hr = nr; hi = ni; }
; #pragma unroll
;         for (int q = 0; q < 16; ++q) { er[q] = nr_[q]; ei[q] = ni_[q]; }
	s_xor_b32 s28, s4, -7
	s_ashr_i32 s27, s26, 31
	v_cvt_pk_bf16_f32 v26, v26, v35
	s_add_i32 s25, s4, 6
	s_add_i32 s28, s28, s22
	s_lshl_b64 s[26:27], s[26:27], 9
	global_store_short v[14:15], v26, off
	v_cvt_pk_bf16_f32 v26, v27, v35
	global_store_short v[14:15], v26, off offset:128
	v_lshl_add_u64 v[14:15], v[10:11], 0, s[26:27]
	s_and_b64 s[26:27], s[6:7], exec
	s_cselect_b32 s26, s25, s28
	s_xor_b32 s28, s4, -8
	s_ashr_i32 s27, s26, 31
	v_cvt_pk_bf16_f32 v26, v40, v35
	s_add_i32 s25, s4, 7
	s_add_i32 s28, s28, s22
	s_lshl_b64 s[26:27], s[26:27], 9
	global_store_short v[14:15], v26, off
	v_cvt_pk_bf16_f32 v26, v38, v35
	global_store_short v[14:15], v26, off offset:128
	v_lshl_add_u64 v[14:15], v[10:11], 0, s[26:27]
	s_and_b64 s[26:27], s[6:7], exec
	s_cselect_b32 s26, s25, s28
	s_xor_b32 s28, s4, -9
	s_ashr_i32 s27, s26, 31
	v_cvt_pk_bf16_f32 v24, v24, v35
	s_add_i32 s25, s4, 8
	s_add_i32 s28, s28, s22
	s_lshl_b64 s[26:27], s[26:27], 9
	global_store_short v[14:15], v24, off
	v_cvt_pk_bf16_f32 v24, v25, v35
	global_store_short v[14:15], v24, off offset:128
	v_lshl_add_u64 v[14:15], v[10:11], 0, s[26:27]
	s_and_b64 s[26:27], s[6:7], exec
	s_cselect_b32 s26, s25, s28
	s_xor_b32 s28, s4, -10
	s_ashr_i32 s27, s26, 31
	v_cvt_pk_bf16_f32 v24, v44, v35
	s_add_i32 s25, s4, 9
	s_add_i32 s28, s28, s22
	s_lshl_b64 s[26:27], s[26:27], 9
	global_store_short v[14:15], v24, off
	v_cvt_pk_bf16_f32 v24, v42, v35
	global_store_short v[14:15], v24, off offset:128
	v_lshl_add_u64 v[14:15], v[10:11], 0, s[26:27]
	s_and_b64 s[26:27], s[6:7], exec
	s_cselect_b32 s26, s25, s28
	s_xor_b32 s28, s4, -11
	s_ashr_i32 s27, s26, 31
	v_cvt_pk_bf16_f32 v22, v22, v35
	s_add_i32 s25, s4, 10
	s_add_i32 s28, s28, s22
	s_lshl_b64 s[26:27], s[26:27], 9
	global_store_short v[14:15], v22, off
	v_cvt_pk_bf16_f32 v22, v23, v35
	global_store_short v[14:15], v22, off offset:128
	v_lshl_add_u64 v[14:15], v[10:11], 0, s[26:27]
	s_and_b64 s[26:27], s[6:7], exec
	s_cselect_b32 s26, s25, s28
	s_xor_b32 s28, s4, -12
	s_ashr_i32 s27, s26, 31
	v_cvt_pk_bf16_f32 v22, v48, v35
	s_add_i32 s25, s4, 11
	s_add_i32 s28, s28, s22
	s_lshl_b64 s[26:27], s[26:27], 9
	global_store_short v[14:15], v22, off
	v_cvt_pk_bf16_f32 v22, v46, v35
	global_store_short v[14:15], v22, off offset:128
	v_lshl_add_u64 v[14:15], v[10:11], 0, s[26:27]
	s_and_b64 s[26:27], s[6:7], exec
	s_cselect_b32 s26, s25, s28
	s_xor_b32 s28, s4, -13
	s_ashr_i32 s27, s26, 31
	v_cvt_pk_bf16_f32 v20, v20, v35
	s_add_i32 s25, s4, 12
	s_add_i32 s28, s28, s22
	s_lshl_b64 s[26:27], s[26:27], 9
	global_store_short v[14:15], v20, off
	v_cvt_pk_bf16_f32 v20, v21, v35
	global_store_short v[14:15], v20, off offset:128
	v_lshl_add_u64 v[14:15], v[10:11], 0, s[26:27]
	s_and_b64 s[26:27], s[6:7], exec
	s_cselect_b32 s26, s25, s28
	s_xor_b32 s28, s4, -14
	s_ashr_i32 s27, s26, 31
	v_cvt_pk_bf16_f32 v20, v52, v35
	s_add_i32 s25, s4, 13
	s_add_i32 s28, s28, s22
	s_lshl_b64 s[26:27], s[26:27], 9
	global_store_short v[14:15], v20, off
	v_cvt_pk_bf16_f32 v20, v50, v35
	global_store_short v[14:15], v20, off offset:128
	v_lshl_add_u64 v[14:15], v[10:11], 0, s[26:27]
	s_and_b64 s[26:27], s[6:7], exec
	s_cselect_b32 s26, s25, s28
	s_xor_b32 s28, s4, -15
	s_ashr_i32 s27, s26, 31
	s_add_i32 s25, s4, 14
	s_add_i32 s28, s28, s22
	s_lshl_b64 s[26:27], s[26:27], 9
	v_cvt_pk_bf16_f32 v19, v19, v35
	global_store_short v[14:15], v19, off
	v_cvt_pk_bf16_f32 v18, v18, v35
	global_store_short v[14:15], v18, off offset:128
	v_lshl_add_u64 v[14:15], v[10:11], 0, s[26:27]
	s_and_b64 s[26:27], s[6:7], exec
	s_cselect_b32 s26, s25, s28
	s_xor_b32 s25, s4, -16
	s_ashr_i32 s27, s26, 31
	v_cvt_pk_bf16_f32 v18, v56, v35
	s_add_i32 s28, s4, 15
	s_mov_b32 s4, s24
	s_add_i32 s29, s25, s22
	s_lshl_b64 s[24:25], s[26:27], 9
	global_store_short v[14:15], v18, off
	v_cvt_pk_bf16_f32 v18, v54, v35
	global_store_short v[14:15], v18, off offset:128
	v_lshl_add_u64 v[14:15], v[10:11], 0, s[24:25]
	s_and_b64 s[24:25], s[6:7], exec
	s_cselect_b32 s24, s28, s29
	s_ashr_i32 s25, s24, 31
	v_cvt_pk_bf16_f32 v17, v17, v35
	global_store_short v[14:15], v17, off
	v_cvt_pk_bf16_f32 v16, v16, v35
	s_and_b64 vcc, s[12:13], exec
	s_lshl_b64 s[12:13], s[24:25], 9
	global_store_short v[14:15], v16, off offset:128
	v_cvt_pk_bf16_f32 v16, v60, v35
	v_lshl_add_u64 v[14:15], v[10:11], 0, s[12:13]
	global_store_short v[14:15], v16, off
	v_cvt_pk_bf16_f32 v16, v58, v35
	s_waitcnt vmcnt(46)
	v_lshlrev_b32_e32 v30, 16, v70
	v_lshlrev_b32_e32 v28, 16, v71
	v_lshlrev_b32_e32 v29, 16, v72
	v_lshlrev_b32_e32 v34, 16, v73
	v_lshlrev_b32_e32 v36, 16, v77
	v_lshlrev_b32_e32 v26, 16, v74
	v_lshlrev_b32_e32 v40, 16, v76
	v_lshlrev_b32_e32 v27, 16, v75
	v_lshlrev_b32_e32 v38, 16, v78
	v_lshlrev_b32_e32 v24, 16, v49
	v_lshlrev_b32_e32 v25, 16, v79
	v_lshlrev_b32_e32 v42, 16, v80
	v_lshlrev_b32_e32 v44, 16, v53
	v_lshlrev_b32_e32 v22, 16, v45
	v_lshlrev_b32_e32 v48, 16, v51
	v_lshlrev_b32_e32 v23, 16, v47
	v_lshlrev_b32_e32 v46, 16, v57
	s_waitcnt vmcnt(45)
	v_lshlrev_b32_e32 v20, 16, v41
	s_waitcnt vmcnt(44)
	v_lshlrev_b32_e32 v21, 16, v43
	s_waitcnt vmcnt(43)
	v_lshlrev_b32_e32 v45, 16, v37
	s_add_i32 s23, s23, -16
	s_waitcnt vmcnt(39)
	v_lshlrev_b32_e32 v49, 16, v61
	v_lshlrev_b32_e32 v19, 16, v39
	v_lshlrev_b32_e32 v47, 16, v59
	v_lshlrev_b32_e32 v18, 16, v55
	global_store_short v[14:15], v16, off offset:128
	s_waitcnt vmcnt(39)
	v_lshlrev_b32_e32 v41, 16, v81
	s_waitcnt vmcnt(38)
	v_lshlrev_b32_e32 v17, 16, v82
	s_waitcnt vmcnt(37)
	v_lshlrev_b32_e32 v16, 16, v83
	s_waitcnt vmcnt(36)
	v_lshlrev_b32_e32 v37, 16, v84
	s_waitcnt vmcnt(32)
	v_lshlrev_b32_e32 v43, 16, v88
	v_lshlrev_b32_e32 v14, 16, v85
	v_lshlrev_b32_e32 v39, 16, v87
	v_lshlrev_b32_e32 v15, 16, v86
	s_cbranch_vccnz .LBB0_588
	s_add_i32 s3, s3, s20
	s_cmpk_gt_i32 s3, 0x3ff
	s_cbranch_scc0 .LBB0_587

; __device__ __forceinline__ unsigned cvt_pk_bf16(float lo, float hi) { unsigned r; asm volatile("v_cvt_pk_bf16_f32 %0, %1, %2" : "=v"(r) : "v"(lo), "v"(hi)); return r; }
; __device__ __forceinline__ float bflo(unsigned w) { return __uint_as_float(w << 16); }
; __device__ __forceinline__ float bfhi(unsigned w) { return __uint_as_float(w & 0xffff0000u); }
; template <bool DRY>
; __device__ __forceinline__ void attn_unit(const Args& a, LAS unsigned char* lds, int cidx, int h, int lane, int wave) {
;     ...
; #pragma unroll
;             for (int gq = 0; gq < 2; ++gq) {
;                 const int qi = qpos[gq] - Pu;
;                 const float dt = den[gq] + *(const float*)((const char*)Xd + (unsigned)qi * 4u) + *(const float*)((const char*)Xd + (unsigned)(512 + qi) * 4u);
;                 const float inv = 1.0f / dt;
;                 const unsigned x1o = ((unsigned)qi * 128 + 4 * fq) * 2u, x4o = ((unsigned)(512 + qi) * 128 + 4 * fq) * 2u;
;                 const unsigned go = ((unsigned)(seq_start + qpos[gq]) * AW + h * 128 + 4 * fq) * 2u;
; #pragma unroll
;                 for (int c = 0; c < 8; ++c) {
;                     bf16_t* gp = (bf16_t*)((char*)GA + go) - 16 * c + 16 * c;
;                     const u32x2 xa = *(const u32x2*)((const char*)X + x1o + 32 * c), xb = *(const u32x2*)((const char*)X + x4o + 32 * c);
;                     const f32x4 t = o[gq][c] + (f32x4){bflo(xa.x), bfhi(xa.x), bflo(xa.y), bfhi(xa.y)} + (f32x4){bflo(xb.x), bfhi(xb.x), bflo(xb.y), bfhi(xb.y)};
;                     const u32x2 gg = *(const u32x2*)(gp + 16 * c);
;                     u32x2 w; w.x = cvt_pk_bf16(t[0] * inv * bflo(gg.x), t[1] * inv * bfhi(gg.x)); w.y = cvt_pk_bf16(t[2] * inv * bflo(gg.y), t[3] * inv * bfhi(gg.y));
;                     if (!DRY || inv == 1.2345e33f) *(u32x2*)(gp + 16 * c) = w;
;                 }
.LBB0_606:
	v_subrev_u32_e32 v76, s50, v190
	v_add_u32_e32 v66, v192, v187
	v_lshlrev_b32_e32 v72, 2, v76
	v_lshl_add_u32 v68, v76, 8, v166
	v_add_u32_e32 v76, 0x200, v76
	v_lshlrev_b32_e32 v73, 2, v76
	v_lshl_add_u32 v69, v76, 8, v166
	v_subrev_u32_e32 v77, s50, v189
	v_add_u32_e32 v67, v191, v187
	v_lshlrev_b32_e32 v74, 2, v77
	v_lshl_add_u32 v70, v77, 8, v166
	v_add_u32_e32 v77, 0x200, v77
	v_lshlrev_b32_e32 v75, 2, v77
	v_lshl_add_u32 v71, v77, 8, v166
	global_load_dword v78, v72, s[30:31]
	global_load_dword v79, v73, s[30:31]
	global_load_dword v80, v74, s[30:31]
	global_load_dword v81, v75, s[30:31]
	global_load_dwordx2 v[96:97], v66, s[20:21]
	global_load_dwordx2 v[98:99], v68, s[22:23]
	global_load_dwordx2 v[100:101], v69, s[22:23]
	global_load_dwordx2 v[102:103], v66, s[20:21] offset:32
	global_load_dwordx2 v[104:105], v68, s[22:23] offset:32
	global_load_dwordx2 v[106:107], v69, s[22:23] offset:32
	global_load_dwordx2 v[108:109], v66, s[20:21] offset:64
	global_load_dwordx2 v[110:111], v68, s[22:23] offset:64
	global_load_dwordx2 v[112:113], v69, s[22:23] offset:64
	global_load_dwordx2 v[114:115], v66, s[20:21] offset:96
	global_load_dwordx2 v[116:117], v68, s[22:23] offset:96
	global_load_dwordx2 v[118:119], v69, s[22:23] offset:96
	global_load_dwordx2 v[120:121], v66, s[20:21] offset:128
	global_load_dwordx2 v[122:123], v68, s[22:23] offset:128
	global_load_dwordx2 v[124:125], v69, s[22:23] offset:128
	global_load_dwordx2 v[126:127], v66, s[20:21] offset:160
	global_load_dwordx2 v[128:129], v68, s[22:23] offset:160
	global_load_dwordx2 v[130:131], v69, s[22:23] offset:160
	global_load_dwordx2 v[132:133], v66, s[20:21] offset:192
	global_load_dwordx2 v[134:135], v68, s[22:23] offset:192
	global_load_dwordx2 v[136:137], v69, s[22:23] offset:192
	global_load_dwordx2 v[138:139], v66, s[20:21] offset:224
	global_load_dwordx2 v[140:141], v68, s[22:23] offset:224
	global_load_dwordx2 v[142:143], v69, s[22:23] offset:224
	global_load_dwordx2 v[144:145], v67, s[20:21]
	global_load_dwordx2 v[146:147], v70, s[22:23]
	global_load_dwordx2 v[148:149], v71, s[22:23]
	global_load_dwordx2 v[150:151], v67, s[20:21] offset:32
	global_load_dwordx2 v[152:153], v70, s[22:23] offset:32
	global_load_dwordx2 v[154:155], v71, s[22:23] offset:32
	global_load_dwordx2 v[156:157], v67, s[20:21] offset:64
	global_load_dwordx2 v[158:159], v70, s[22:23] offset:64
	global_load_dwordx2 v[194:195], v71, s[22:23] offset:64
	global_load_dwordx2 v[196:197], v67, s[20:21] offset:96
	global_load_dwordx2 v[198:199], v70, s[22:23] offset:96
	global_load_dwordx2 v[200:201], v71, s[22:23] offset:96
	global_load_dwordx2 v[202:203], v67, s[20:21] offset:128
	global_load_dwordx2 v[204:205], v70, s[22:23] offset:128
	global_load_dwordx2 v[206:207], v71, s[22:23] offset:128
	global_load_dwordx2 v[208:209], v67, s[20:21] offset:160
	global_load_dwordx2 v[210:211], v70, s[22:23] offset:160
	global_load_dwordx2 v[212:213], v71, s[22:23] offset:160
	global_load_dwordx2 v[214:215], v67, s[20:21] offset:192
	global_load_dwordx2 v[216:217], v70, s[22:23] offset:192
	global_load_dwordx2 v[218:219], v71, s[22:23] offset:192
	global_load_dwordx2 v[220:221], v67, s[20:21] offset:224
	global_load_dwordx2 v[222:223], v70, s[22:23] offset:224
	global_load_dwordx2 v[224:225], v71, s[22:23] offset:224
	s_waitcnt vmcnt(50)
	v_add_f32_e32 v92, v65, v78
	v_add_f32_e32 v92, v92, v79
	s_waitcnt vmcnt(48)
	v_add_f32_e32 v93, v64, v80
	v_add_f32_e32 v93, v93, v81
	v_div_scale_f32 v84, s[6:7], v92, v92, 1.0
	v_rcp_f32_e32 v85, v84
	v_div_scale_f32 v86, vcc, 1.0, v92, 1.0
	v_fma_f32 v87, -v84, v85, 1.0
	v_fmac_f32_e32 v85, v87, v85
	v_mul_f32_e32 v87, v86, v85
	v_fma_f32 v88, -v84, v87, v86
	v_fmac_f32_e32 v87, v88, v85
	v_fma_f32 v88, -v84, v87, v86
	v_div_fmas_f32 v87, v88, v85, v87
	v_div_fixup_f32 v82, v87, v92, 1.0
	v_div_scale_f32 v84, s[6:7], v93, v93, 1.0
	v_rcp_f32_e32 v85, v84
	v_div_scale_f32 v86, vcc, 1.0, v93, 1.0
	v_fma_f32 v87, -v84, v85, 1.0
	v_fmac_f32_e32 v85, v87, v85
	v_mul_f32_e32 v87, v86, v85
	v_fma_f32 v88, -v84, v87, v86
	v_fmac_f32_e32 v87, v88, v85
	v_fma_f32 v88, -v84, v87, v86
	v_div_fmas_f32 v87, v88, v85, v87
	v_div_fixup_f32 v83, v87, v93, 1.0
	s_waitcnt vmcnt(45)
	v_lshlrev_b32_e32 v84, 16, v98
	v_and_b32_e32 v85, 0xffff0000, v98
	v_lshlrev_b32_e32 v86, 16, v99
	v_and_b32_e32 v87, 0xffff0000, v99
	v_lshlrev_b32_e32 v88, 16, v100
	v_and_b32_e32 v89, 0xffff0000, v100
	v_lshlrev_b32_e32 v90, 16, v101
	v_and_b32_e32 v91, 0xffff0000, v101
	v_pk_add_f32 v[84:85], v[60:61], v[84:85]
	v_pk_add_f32 v[86:87], v[62:63], v[86:87]
	v_pk_add_f32 v[84:85], v[84:85], v[88:89]
	v_pk_add_f32 v[86:87], v[86:87], v[90:91]
	v_mul_f32_e32 v84, v82, v84
	v_mul_f32_e32 v85, v82, v85
	v_mul_f32_e32 v86, v82, v86
	v_mul_f32_e32 v87, v82, v87
	v_lshlrev_b32_e32 v88, 16, v96
	v_and_b32_e32 v89, 0xffff0000, v96
	v_lshlrev_b32_e32 v90, 16, v97
	v_and_b32_e32 v91, 0xffff0000, v97
	v_mul_f32_e32 v84, v84, v88
	v_mul_f32_e32 v85, v85, v89
	v_mul_f32_e32 v86, v86, v90
	v_mul_f32_e32 v87, v87, v91
	v_cvt_pk_bf16_f32 v84, v84, v85
	v_cvt_pk_bf16_f32 v85, v86, v87
	global_store_dwordx2 v66, v[84:85], s[20:21]
	s_waitcnt vmcnt(43)
; __device__ __forceinline__ unsigned cvt_pk_bf16(float lo, float hi) { unsigned r; asm volatile("v_cvt_pk_bf16_f32 %0, %1, %2" : "=v"(r) : "v"(lo), "v"(hi)); return r; }
; __device__ __forceinline__ float bflo(unsigned w) { return __uint_as_float(w << 16); }
; __device__ __forceinline__ float bfhi(unsigned w) { return __uint_as_float(w & 0xffff0000u); }
; template <bool DRY>
; __device__ __forceinline__ void attn_unit(const Args& a, LAS unsigned char* lds, int cidx, int h, int lane, int wave) {
;     ...
; #pragma unroll
;                 for (int c = 0; c < 8; ++c) {
;                     bf16_t* gp = (bf16_t*)((char*)GA + go) - 16 * c + 16 * c;
;                     const u32x2 xa = *(const u32x2*)((const char*)X + x1o + 32 * c), xb = *(const u32x2*)((const char*)X + x4o + 32 * c);
;                     const f32x4 t = o[gq][c] + (f32x4){bflo(xa.x), bfhi(xa.x), bflo(xa.y), bfhi(xa.y)} + (f32x4){bflo(xb.x), bfhi(xb.x), bflo(xb.y), bfhi(xb.y)};
;                     const u32x2 gg = *(const u32x2*)(gp + 16 * c);
;                     u32x2 w; w.x = cvt_pk_bf16(t[0] * inv * bflo(gg.x), t[1] * inv * bfhi(gg.x)); w.y = cvt_pk_bf16(t[2] * inv * bflo(gg.y), t[3] * inv * bfhi(gg.y));
;                     if (!DRY || inv == 1.2345e33f) *(u32x2*)(gp + 16 * c) = w;
;                 }
	v_lshlrev_b32_e32 v84, 16, v104
	v_and_b32_e32 v85, 0xffff0000, v104
	v_lshlrev_b32_e32 v86, 16, v105
	v_and_b32_e32 v87, 0xffff0000, v105
	v_lshlrev_b32_e32 v88, 16, v106
	v_and_b32_e32 v89, 0xffff0000, v106
	v_lshlrev_b32_e32 v90, 16, v107
	v_and_b32_e32 v91, 0xffff0000, v107
	v_pk_add_f32 v[84:85], v[40:41], v[84:85]
	v_pk_add_f32 v[86:87], v[42:43], v[86:87]
	v_pk_add_f32 v[84:85], v[84:85], v[88:89]
	v_pk_add_f32 v[86:87], v[86:87], v[90:91]
	v_mul_f32_e32 v84, v82, v84
	v_mul_f32_e32 v85, v82, v85
	v_mul_f32_e32 v86, v82, v86
	v_mul_f32_e32 v87, v82, v87
	v_lshlrev_b32_e32 v88, 16, v102
	v_and_b32_e32 v89, 0xffff0000, v102
	v_lshlrev_b32_e32 v90, 16, v103
	v_and_b32_e32 v91, 0xffff0000, v103
	v_mul_f32_e32 v84, v84, v88
	v_mul_f32_e32 v85, v85, v89
	v_mul_f32_e32 v86, v86, v90
	v_mul_f32_e32 v87, v87, v91
	v_cvt_pk_bf16_f32 v84, v84, v85
	v_cvt_pk_bf16_f32 v85, v86, v87
	global_store_dwordx2 v66, v[84:85], s[20:21] offset:32
	s_waitcnt vmcnt(41)
	v_lshlrev_b32_e32 v84, 16, v110
	v_and_b32_e32 v85, 0xffff0000, v110
	v_lshlrev_b32_e32 v86, 16, v111
	v_and_b32_e32 v87, 0xffff0000, v111
	v_lshlrev_b32_e32 v88, 16, v112
	v_and_b32_e32 v89, 0xffff0000, v112
	v_lshlrev_b32_e32 v90, 16, v113
	v_and_b32_e32 v91, 0xffff0000, v113
	v_pk_add_f32 v[84:85], v[56:57], v[84:85]
	v_pk_add_f32 v[86:87], v[58:59], v[86:87]
	v_pk_add_f32 v[84:85], v[84:85], v[88:89]
	v_pk_add_f32 v[86:87], v[86:87], v[90:91]
	v_mul_f32_e32 v84, v82, v84
	v_mul_f32_e32 v85, v82, v85
	v_mul_f32_e32 v86, v82, v86
	v_mul_f32_e32 v87, v82, v87
	v_lshlrev_b32_e32 v88, 16, v108
	v_and_b32_e32 v89, 0xffff0000, v108
	v_lshlrev_b32_e32 v90, 16, v109
	v_and_b32_e32 v91, 0xffff0000, v109
	v_mul_f32_e32 v84, v84, v88
	v_mul_f32_e32 v85, v85, v89
	v_mul_f32_e32 v86, v86, v90
	v_mul_f32_e32 v87, v87, v91
	v_cvt_pk_bf16_f32 v84, v84, v85
	v_cvt_pk_bf16_f32 v85, v86, v87
	global_store_dwordx2 v66, v[84:85], s[20:21] offset:64
	s_waitcnt vmcnt(39)
	v_lshlrev_b32_e32 v84, 16, v116
	v_and_b32_e32 v85, 0xffff0000, v116
	v_lshlrev_b32_e32 v86, 16, v117
	v_and_b32_e32 v87, 0xffff0000, v117
	v_lshlrev_b32_e32 v88, 16, v118
	v_and_b32_e32 v89, 0xffff0000, v118
	v_lshlrev_b32_e32 v90, 16, v119
	v_and_b32_e32 v91, 0xffff0000, v119
	v_pk_add_f32 v[84:85], v[52:53], v[84:85]
	v_pk_add_f32 v[86:87], v[54:55], v[86:87]
	v_pk_add_f32 v[84:85], v[84:85], v[88:89]
	v_pk_add_f32 v[86:87], v[86:87], v[90:91]
	v_mul_f32_e32 v84, v82, v84
	v_mul_f32_e32 v85, v82, v85
	v_mul_f32_e32 v86, v82, v86
	v_mul_f32_e32 v87, v82, v87
	v_lshlrev_b32_e32 v88, 16, v114
	v_and_b32_e32 v89, 0xffff0000, v114
	v_lshlrev_b32_e32 v90, 16, v115
	v_and_b32_e32 v91, 0xffff0000, v115
	v_mul_f32_e32 v84, v84, v88
	v_mul_f32_e32 v85, v85, v89
	v_mul_f32_e32 v86, v86, v90
	v_mul_f32_e32 v87, v87, v91
	v_cvt_pk_bf16_f32 v84, v84, v85
	v_cvt_pk_bf16_f32 v85, v86, v87
	global_store_dwordx2 v66, v[84:85], s[20:21] offset:96
	s_waitcnt vmcnt(37)
	v_lshlrev_b32_e32 v84, 16, v122
	v_and_b32_e32 v85, 0xffff0000, v122
	v_lshlrev_b32_e32 v86, 16, v123
	v_and_b32_e32 v87, 0xffff0000, v123
	v_lshlrev_b32_e32 v88, 16, v124
	v_and_b32_e32 v89, 0xffff0000, v124
	v_lshlrev_b32_e32 v90, 16, v125
	v_and_b32_e32 v91, 0xffff0000, v125
	v_pk_add_f32 v[84:85], v[48:49], v[84:85]
	v_pk_add_f32 v[86:87], v[50:51], v[86:87]
	v_pk_add_f32 v[84:85], v[84:85], v[88:89]
	v_pk_add_f32 v[86:87], v[86:87], v[90:91]
	v_mul_f32_e32 v84, v82, v84
	v_mul_f32_e32 v85, v82, v85
	v_mul_f32_e32 v86, v82, v86
	v_mul_f32_e32 v87, v82, v87
	v_lshlrev_b32_e32 v88, 16, v120
	v_and_b32_e32 v89, 0xffff0000, v120
	v_lshlrev_b32_e32 v90, 16, v121
	v_and_b32_e32 v91, 0xffff0000, v121
	v_mul_f32_e32 v84, v84, v88
	v_mul_f32_e32 v85, v85, v89
	v_mul_f32_e32 v86, v86, v90
	v_mul_f32_e32 v87, v87, v91
	v_cvt_pk_bf16_f32 v84, v84, v85
	v_cvt_pk_bf16_f32 v85, v86, v87
	global_store_dwordx2 v66, v[84:85], s[20:21] offset:128
	s_waitcnt vmcnt(35)
	v_lshlrev_b32_e32 v84, 16, v128
	v_and_b32_e32 v85, 0xffff0000, v128
	v_lshlrev_b32_e32 v86, 16, v129
	v_and_b32_e32 v87, 0xffff0000, v129
	v_lshlrev_b32_e32 v88, 16, v130
	v_and_b32_e32 v89, 0xffff0000, v130
	v_lshlrev_b32_e32 v90, 16, v131
	v_and_b32_e32 v91, 0xffff0000, v131
	v_pk_add_f32 v[84:85], v[44:45], v[84:85]
	v_pk_add_f32 v[86:87], v[46:47], v[86:87]
	v_pk_add_f32 v[84:85], v[84:85], v[88:89]
	v_pk_add_f32 v[86:87], v[86:87], v[90:91]
	v_mul_f32_e32 v84, v82, v84
	v_mul_f32_e32 v85, v82, v85
	v_mul_f32_e32 v86, v82, v86
	v_mul_f32_e32 v87, v82, v87
	v_lshlrev_b32_e32 v88, 16, v126
	v_and_b32_e32 v89, 0xffff0000, v126
	v_lshlrev_b32_e32 v90, 16, v127
	v_and_b32_e32 v91, 0xffff0000, v127
	v_mul_f32_e32 v84, v84, v88
	v_mul_f32_e32 v85, v85, v89
	v_mul_f32_e32 v86, v86, v90
	v_mul_f32_e32 v87, v87, v91
	v_cvt_pk_bf16_f32 v84, v84, v85
	v_cvt_pk_bf16_f32 v85, v86, v87
	global_store_dwordx2 v66, v[84:85], s[20:21] offset:160
	s_waitcnt vmcnt(33)
	v_lshlrev_b32_e32 v84, 16, v134
	v_and_b32_e32 v85, 0xffff0000, v134
	v_lshlrev_b32_e32 v86, 16, v135
	v_and_b32_e32 v87, 0xffff0000, v135
	v_lshlrev_b32_e32 v88, 16, v136
	v_and_b32_e32 v89, 0xffff0000, v136
	v_lshlrev_b32_e32 v90, 16, v137
	v_and_b32_e32 v91, 0xffff0000, v137
	v_pk_add_f32 v[84:85], v[36:37], v[84:85]
	v_pk_add_f32 v[86:87], v[38:39], v[86:87]
	v_pk_add_f32 v[84:85], v[84:85], v[88:89]
	v_pk_add_f32 v[86:87], v[86:87], v[90:91]
	v_mul_f32_e32 v84, v82, v84
	v_mul_f32_e32 v85, v82, v85
	v_mul_f32_e32 v86, v82, v86
	v_mul_f32_e32 v87, v82, v87
	v_lshlrev_b32_e32 v88, 16, v132
	v_and_b32_e32 v89, 0xffff0000, v132
	v_lshlrev_b32_e32 v90, 16, v133
	v_and_b32_e32 v91, 0xffff0000, v133
	v_mul_f32_e32 v84, v84, v88
	v_mul_f32_e32 v85, v85, v89
	v_mul_f32_e32 v86, v86, v90
	v_mul_f32_e32 v87, v87, v91
	v_cvt_pk_bf16_f32 v84, v84, v85
	v_cvt_pk_bf16_f32 v85, v86, v87
	global_store_dwordx2 v66, v[84:85], s[20:21] offset:192
	s_waitcnt vmcnt(31)
; __device__ __forceinline__ unsigned cvt_pk_bf16(float lo, float hi) { unsigned r; asm volatile("v_cvt_pk_bf16_f32 %0, %1, %2" : "=v"(r) : "v"(lo), "v"(hi)); return r; }
; __device__ __forceinline__ float bflo(unsigned w) { return __uint_as_float(w << 16); }
; __device__ __forceinline__ float bfhi(unsigned w) { return __uint_as_float(w & 0xffff0000u); }
; template <bool DRY>
; __device__ __forceinline__ void attn_unit(const Args& a, LAS unsigned char* lds, int cidx, int h, int lane, int wave) {
;     ...
; #pragma unroll
;                 for (int c = 0; c < 8; ++c) {
;                     bf16_t* gp = (bf16_t*)((char*)GA + go) - 16 * c + 16 * c;
;                     const u32x2 xa = *(const u32x2*)((const char*)X + x1o + 32 * c), xb = *(const u32x2*)((const char*)X + x4o + 32 * c);
;                     const f32x4 t = o[gq][c] + (f32x4){bflo(xa.x), bfhi(xa.x), bflo(xa.y), bfhi(xa.y)} + (f32x4){bflo(xb.x), bfhi(xb.x), bflo(xb.y), bfhi(xb.y)};
;                     const u32x2 gg = *(const u32x2*)(gp + 16 * c);
;                     u32x2 w; w.x = cvt_pk_bf16(t[0] * inv * bflo(gg.x), t[1] * inv * bfhi(gg.x)); w.y = cvt_pk_bf16(t[2] * inv * bflo(gg.y), t[3] * inv * bfhi(gg.y));
;                     if (!DRY || inv == 1.2345e33f) *(u32x2*)(gp + 16 * c) = w;
;                 }
	v_lshlrev_b32_e32 v84, 16, v140
	v_and_b32_e32 v85, 0xffff0000, v140
	v_lshlrev_b32_e32 v86, 16, v141
	v_and_b32_e32 v87, 0xffff0000, v141
	v_lshlrev_b32_e32 v88, 16, v142
	v_and_b32_e32 v89, 0xffff0000, v142
	v_lshlrev_b32_e32 v90, 16, v143
	v_and_b32_e32 v91, 0xffff0000, v143
	v_pk_add_f32 v[84:85], v[32:33], v[84:85]
	v_pk_add_f32 v[86:87], v[34:35], v[86:87]
	v_pk_add_f32 v[84:85], v[84:85], v[88:89]
	v_pk_add_f32 v[86:87], v[86:87], v[90:91]
	v_mul_f32_e32 v84, v82, v84
	v_mul_f32_e32 v85, v82, v85
	v_mul_f32_e32 v86, v82, v86
	v_mul_f32_e32 v87, v82, v87
	v_lshlrev_b32_e32 v88, 16, v138
	v_and_b32_e32 v89, 0xffff0000, v138
	v_lshlrev_b32_e32 v90, 16, v139
	v_and_b32_e32 v91, 0xffff0000, v139
	v_mul_f32_e32 v84, v84, v88
	v_mul_f32_e32 v85, v85, v89
	v_mul_f32_e32 v86, v86, v90
	v_mul_f32_e32 v87, v87, v91
	v_cvt_pk_bf16_f32 v84, v84, v85
	v_cvt_pk_bf16_f32 v85, v86, v87
	global_store_dwordx2 v66, v[84:85], s[20:21] offset:224
	s_waitcnt vmcnt(29)
	v_lshlrev_b32_e32 v84, 16, v146
	v_and_b32_e32 v85, 0xffff0000, v146
	v_lshlrev_b32_e32 v86, 16, v147
	v_and_b32_e32 v87, 0xffff0000, v147
	v_lshlrev_b32_e32 v88, 16, v148
	v_and_b32_e32 v89, 0xffff0000, v148
	v_lshlrev_b32_e32 v90, 16, v149
	v_and_b32_e32 v91, 0xffff0000, v149
	v_pk_add_f32 v[84:85], v[28:29], v[84:85]
	v_pk_add_f32 v[86:87], v[30:31], v[86:87]
	v_pk_add_f32 v[84:85], v[84:85], v[88:89]
	v_pk_add_f32 v[86:87], v[86:87], v[90:91]
	v_mul_f32_e32 v84, v83, v84
	v_mul_f32_e32 v85, v83, v85
	v_mul_f32_e32 v86, v83, v86
	v_mul_f32_e32 v87, v83, v87
	v_lshlrev_b32_e32 v88, 16, v144
	v_and_b32_e32 v89, 0xffff0000, v144
	v_lshlrev_b32_e32 v90, 16, v145
	v_and_b32_e32 v91, 0xffff0000, v145
	v_mul_f32_e32 v84, v84, v88
	v_mul_f32_e32 v85, v85, v89
	v_mul_f32_e32 v86, v86, v90
	v_mul_f32_e32 v87, v87, v91
	v_cvt_pk_bf16_f32 v84, v84, v85
	v_cvt_pk_bf16_f32 v85, v86, v87
	global_store_dwordx2 v67, v[84:85], s[20:21]
	s_waitcnt vmcnt(27)
	v_lshlrev_b32_e32 v84, 16, v152
	v_and_b32_e32 v85, 0xffff0000, v152
	v_lshlrev_b32_e32 v86, 16, v153
	v_and_b32_e32 v87, 0xffff0000, v153
	v_lshlrev_b32_e32 v88, 16, v154
	v_and_b32_e32 v89, 0xffff0000, v154
	v_lshlrev_b32_e32 v90, 16, v155
	v_and_b32_e32 v91, 0xffff0000, v155
	v_pk_add_f32 v[84:85], v[24:25], v[84:85]
	v_pk_add_f32 v[86:87], v[26:27], v[86:87]
	v_pk_add_f32 v[84:85], v[84:85], v[88:89]
	v_pk_add_f32 v[86:87], v[86:87], v[90:91]
	v_mul_f32_e32 v84, v83, v84
	v_mul_f32_e32 v85, v83, v85
	v_mul_f32_e32 v86, v83, v86
	v_mul_f32_e32 v87, v83, v87
	v_lshlrev_b32_e32 v88, 16, v150
	v_and_b32_e32 v89, 0xffff0000, v150
	v_lshlrev_b32_e32 v90, 16, v151
	v_and_b32_e32 v91, 0xffff0000, v151
	v_mul_f32_e32 v84, v84, v88
	v_mul_f32_e32 v85, v85, v89
	v_mul_f32_e32 v86, v86, v90
	v_mul_f32_e32 v87, v87, v91
	v_cvt_pk_bf16_f32 v84, v84, v85
	v_cvt_pk_bf16_f32 v85, v86, v87
	global_store_dwordx2 v67, v[84:85], s[20:21] offset:32
	s_waitcnt vmcnt(25)
	v_lshlrev_b32_e32 v84, 16, v158
	v_and_b32_e32 v85, 0xffff0000, v158
	v_lshlrev_b32_e32 v86, 16, v159
	v_and_b32_e32 v87, 0xffff0000, v159
	v_lshlrev_b32_e32 v88, 16, v194
	v_and_b32_e32 v89, 0xffff0000, v194
	v_lshlrev_b32_e32 v90, 16, v195
	v_and_b32_e32 v91, 0xffff0000, v195
	v_pk_add_f32 v[84:85], v[20:21], v[84:85]
	v_pk_add_f32 v[86:87], v[22:23], v[86:87]
	v_pk_add_f32 v[84:85], v[84:85], v[88:89]
	v_pk_add_f32 v[86:87], v[86:87], v[90:91]
	v_mul_f32_e32 v84, v83, v84
	v_mul_f32_e32 v85, v83, v85
	v_mul_f32_e32 v86, v83, v86
	v_mul_f32_e32 v87, v83, v87
	v_lshlrev_b32_e32 v88, 16, v156
	v_and_b32_e32 v89, 0xffff0000, v156
	v_lshlrev_b32_e32 v90, 16, v157
	v_and_b32_e32 v91, 0xffff0000, v157
	v_mul_f32_e32 v84, v84, v88
	v_mul_f32_e32 v85, v85, v89
	v_mul_f32_e32 v86, v86, v90
	v_mul_f32_e32 v87, v87, v91
	v_cvt_pk_bf16_f32 v84, v84, v85
	v_cvt_pk_bf16_f32 v85, v86, v87
	global_store_dwordx2 v67, v[84:85], s[20:21] offset:64
	s_waitcnt vmcnt(23)
	v_lshlrev_b32_e32 v84, 16, v198
	v_and_b32_e32 v85, 0xffff0000, v198
	v_lshlrev_b32_e32 v86, 16, v199
	v_and_b32_e32 v87, 0xffff0000, v199
	v_lshlrev_b32_e32 v88, 16, v200
	v_and_b32_e32 v89, 0xffff0000, v200
	v_lshlrev_b32_e32 v90, 16, v201
	v_and_b32_e32 v91, 0xffff0000, v201
	v_pk_add_f32 v[84:85], v[16:17], v[84:85]
	v_pk_add_f32 v[86:87], v[18:19], v[86:87]
	v_pk_add_f32 v[84:85], v[84:85], v[88:89]
	v_pk_add_f32 v[86:87], v[86:87], v[90:91]
	v_mul_f32_e32 v84, v83, v84
	v_mul_f32_e32 v85, v83, v85
	v_mul_f32_e32 v86, v83, v86
	v_mul_f32_e32 v87, v83, v87
	v_lshlrev_b32_e32 v88, 16, v196
	v_and_b32_e32 v89, 0xffff0000, v196
	v_lshlrev_b32_e32 v90, 16, v197
	v_and_b32_e32 v91, 0xffff0000, v197
	v_mul_f32_e32 v84, v84, v88
	v_mul_f32_e32 v85, v85, v89
	v_mul_f32_e32 v86, v86, v90
	v_mul_f32_e32 v87, v87, v91
	v_cvt_pk_bf16_f32 v84, v84, v85
	v_cvt_pk_bf16_f32 v85, v86, v87
	global_store_dwordx2 v67, v[84:85], s[20:21] offset:96
	s_waitcnt vmcnt(21)
; __device__ __forceinline__ unsigned cvt_pk_bf16(float lo, float hi) { unsigned r; asm volatile("v_cvt_pk_bf16_f32 %0, %1, %2" : "=v"(r) : "v"(lo), "v"(hi)); return r; }
; __device__ __forceinline__ float bflo(unsigned w) { return __uint_as_float(w << 16); }
; __device__ __forceinline__ float bfhi(unsigned w) { return __uint_as_float(w & 0xffff0000u); }
; template <bool DRY>
; __device__ __forceinline__ void attn_unit(const Args& a, LAS unsigned char* lds, int cidx, int h, int lane, int wave) {
;     ...
; #pragma unroll
;                 for (int c = 0; c < 8; ++c) {
;                     bf16_t* gp = (bf16_t*)((char*)GA + go) - 16 * c + 16 * c;
;                     const u32x2 xa = *(const u32x2*)((const char*)X + x1o + 32 * c), xb = *(const u32x2*)((const char*)X + x4o + 32 * c);
;                     const f32x4 t = o[gq][c] + (f32x4){bflo(xa.x), bfhi(xa.x), bflo(xa.y), bfhi(xa.y)} + (f32x4){bflo(xb.x), bfhi(xb.x), bflo(xb.y), bfhi(xb.y)};
;                     const u32x2 gg = *(const u32x2*)(gp + 16 * c);
;                     u32x2 w; w.x = cvt_pk_bf16(t[0] * inv * bflo(gg.x), t[1] * inv * bfhi(gg.x)); w.y = cvt_pk_bf16(t[2] * inv * bflo(gg.y), t[3] * inv * bfhi(gg.y));
;                     if (!DRY || inv == 1.2345e33f) *(u32x2*)(gp + 16 * c) = w;
;                 }
	v_lshlrev_b32_e32 v84, 16, v204
	v_and_b32_e32 v85, 0xffff0000, v204
	v_lshlrev_b32_e32 v86, 16, v205
	v_and_b32_e32 v87, 0xffff0000, v205
	v_lshlrev_b32_e32 v88, 16, v206
	v_and_b32_e32 v89, 0xffff0000, v206
	v_lshlrev_b32_e32 v90, 16, v207
	v_and_b32_e32 v91, 0xffff0000, v207
	v_pk_add_f32 v[84:85], v[12:13], v[84:85]
	v_pk_add_f32 v[86:87], v[14:15], v[86:87]
	v_pk_add_f32 v[84:85], v[84:85], v[88:89]
	v_pk_add_f32 v[86:87], v[86:87], v[90:91]
	v_mul_f32_e32 v84, v83, v84
	v_mul_f32_e32 v85, v83, v85
	v_mul_f32_e32 v86, v83, v86
	v_mul_f32_e32 v87, v83, v87
	v_lshlrev_b32_e32 v88, 16, v202
	v_and_b32_e32 v89, 0xffff0000, v202
	v_lshlrev_b32_e32 v90, 16, v203
	v_and_b32_e32 v91, 0xffff0000, v203
	v_mul_f32_e32 v84, v84, v88
	v_mul_f32_e32 v85, v85, v89
	v_mul_f32_e32 v86, v86, v90
	v_mul_f32_e32 v87, v87, v91
	v_cvt_pk_bf16_f32 v84, v84, v85
	v_cvt_pk_bf16_f32 v85, v86, v87
	global_store_dwordx2 v67, v[84:85], s[20:21] offset:128
	s_waitcnt vmcnt(19)
	v_lshlrev_b32_e32 v84, 16, v210
	v_and_b32_e32 v85, 0xffff0000, v210
	v_lshlrev_b32_e32 v86, 16, v211
	v_and_b32_e32 v87, 0xffff0000, v211
	v_lshlrev_b32_e32 v88, 16, v212
	v_and_b32_e32 v89, 0xffff0000, v212
	v_lshlrev_b32_e32 v90, 16, v213
	v_and_b32_e32 v91, 0xffff0000, v213
	v_pk_add_f32 v[84:85], v[8:9], v[84:85]
	v_pk_add_f32 v[86:87], v[10:11], v[86:87]
	v_pk_add_f32 v[84:85], v[84:85], v[88:89]
	v_pk_add_f32 v[86:87], v[86:87], v[90:91]
	v_mul_f32_e32 v84, v83, v84
	v_mul_f32_e32 v85, v83, v85
	v_mul_f32_e32 v86, v83, v86
	v_mul_f32_e32 v87, v83, v87
	v_lshlrev_b32_e32 v88, 16, v208
	v_and_b32_e32 v89, 0xffff0000, v208
	v_lshlrev_b32_e32 v90, 16, v209
	v_and_b32_e32 v91, 0xffff0000, v209
	v_mul_f32_e32 v84, v84, v88
	v_mul_f32_e32 v85, v85, v89
	v_mul_f32_e32 v86, v86, v90
	v_mul_f32_e32 v87, v87, v91
	v_cvt_pk_bf16_f32 v84, v84, v85
	v_cvt_pk_bf16_f32 v85, v86, v87
	global_store_dwordx2 v67, v[84:85], s[20:21] offset:160
	s_waitcnt vmcnt(17)
	v_lshlrev_b32_e32 v84, 16, v216
	v_and_b32_e32 v85, 0xffff0000, v216
	v_lshlrev_b32_e32 v86, 16, v217
	v_and_b32_e32 v87, 0xffff0000, v217
	v_lshlrev_b32_e32 v88, 16, v218
	v_and_b32_e32 v89, 0xffff0000, v218
	v_lshlrev_b32_e32 v90, 16, v219
	v_and_b32_e32 v91, 0xffff0000, v219
	v_pk_add_f32 v[84:85], v[4:5], v[84:85]
	v_pk_add_f32 v[86:87], v[6:7], v[86:87]
	v_pk_add_f32 v[84:85], v[84:85], v[88:89]
	v_pk_add_f32 v[86:87], v[86:87], v[90:91]
	v_mul_f32_e32 v84, v83, v84
	v_mul_f32_e32 v85, v83, v85
	v_mul_f32_e32 v86, v83, v86
	v_mul_f32_e32 v87, v83, v87
	v_lshlrev_b32_e32 v88, 16, v214
	v_and_b32_e32 v89, 0xffff0000, v214
	v_lshlrev_b32_e32 v90, 16, v215
	v_and_b32_e32 v91, 0xffff0000, v215
	v_mul_f32_e32 v84, v84, v88
	v_mul_f32_e32 v85, v85, v89
	v_mul_f32_e32 v86, v86, v90
	v_mul_f32_e32 v87, v87, v91
	v_cvt_pk_bf16_f32 v84, v84, v85
	v_cvt_pk_bf16_f32 v85, v86, v87
	global_store_dwordx2 v67, v[84:85], s[20:21] offset:192
	s_waitcnt vmcnt(15)
	v_lshlrev_b32_e32 v84, 16, v222
	v_and_b32_e32 v85, 0xffff0000, v222
	v_lshlrev_b32_e32 v86, 16, v223
	v_and_b32_e32 v87, 0xffff0000, v223
	v_lshlrev_b32_e32 v88, 16, v224
	v_and_b32_e32 v89, 0xffff0000, v224
	v_lshlrev_b32_e32 v90, 16, v225
	v_and_b32_e32 v91, 0xffff0000, v225
	v_pk_add_f32 v[84:85], v[0:1], v[84:85]
	v_pk_add_f32 v[86:87], v[2:3], v[86:87]
	v_pk_add_f32 v[84:85], v[84:85], v[88:89]
	v_pk_add_f32 v[86:87], v[86:87], v[90:91]
	v_mul_f32_e32 v84, v83, v84
	v_mul_f32_e32 v85, v83, v85
	v_mul_f32_e32 v86, v83, v86
	v_mul_f32_e32 v87, v83, v87
	v_lshlrev_b32_e32 v88, 16, v220
	v_and_b32_e32 v89, 0xffff0000, v220
	v_lshlrev_b32_e32 v90, 16, v221
	v_and_b32_e32 v91, 0xffff0000, v221
	v_mul_f32_e32 v84, v84, v88
	v_mul_f32_e32 v85, v85, v89
	v_mul_f32_e32 v86, v86, v90
	v_mul_f32_e32 v87, v87, v91
	v_cvt_pk_bf16_f32 v84, v84, v85
	v_cvt_pk_bf16_f32 v85, v86, v87
	global_store_dwordx2 v67, v[84:85], s[20:21] offset:224
	s_branch .LBB0_595
